# P0: bias load issued with the item's other loads; P1 hconv: gain/scale/shift vectors of chunks 1-3 loaded at the top of the row iteration instead of one chunk at a time behind the previous chunk's sto
# speedup vs baseline: 1.0013x; 1.0013x over previous
.LBB0_9:
	global_load_dword v66, v[30:31], off
	global_load_dword v67, v[30:31], off offset:2048
	s_ashr_i32 s11, s10, 31
	s_lshl_b64 s[12:13], s[10:11], 2
	s_add_u32 s12, s64, s12
	s_addc_u32 s13, s65, s13
	v_lshl_add_u64 v[62:63], s[12:13], 0, v[26:27]
	v_lshl_add_u64 v[64:65], s[12:13], 0, v[28:29]
	global_load_dwordx4 v[18:21], v[62:63], off
	global_load_dwordx4 v[22:25], v[64:65], off
	global_load_dword v58, v[34:35], off
	global_load_dword v56, v[36:37], off
	global_load_dword v60, v[32:33], off
	global_load_dword v61, v[40:41], off
	global_load_dword v59, v[42:43], off
	global_load_dword v57, v[44:45], off
	global_load_dword v55, v[38:39], off
	global_load_dword v54, v[38:39], off offset:2048
	global_load_dwordx4 v[10:13], v[62:63], off offset:16
	global_load_dwordx4 v[2:5], v[62:63], off offset:32
	global_load_dwordx4 v[6:9], v[64:65], off offset:32
	global_load_dwordx4 v[14:17], v[64:65], off offset:16
	s_and_saveexec_b64 s[12:13], s[4:5]
	v_add_u32_e32 v100, s10, v52
	v_ashrrev_i32_e32 v101, 31, v100
	v_lshl_add_u64 v[100:101], v[100:101], 2, s[66:67]
	global_load_dword v99, v[100:101], off
	s_mov_b64 exec, s[12:13]
	s_waitcnt vmcnt(15)
	v_mul_f32_e32 v62, 0xbfb8aa3b, v66
	s_waitcnt vmcnt(14)
	v_mul_f32_e32 v63, 0xbfb8aa3b, v67
	v_exp_f32_e32 v62, v62
	v_exp_f32_e32 v63, v63
	v_add_f32_e32 v62, 1.0, v62
	v_add_f32_e32 v63, 1.0, v63
	v_rcp_f32_e32 v62, v62
	v_rcp_f32_e32 v64, v63
	v_mul_f32_e32 v63, v66, v62
	v_mul_f32_e32 v62, v67, v64
	s_waitcnt vmcnt(13)
	v_fma_f32 v68, v63, v18, 0
	s_waitcnt vmcnt(12)
	v_fmac_f32_e32 v68, v62, v22
	v_fma_f32 v69, v63, v19, 0
	v_fmac_f32_e32 v69, v62, v23
	v_fma_f32 v70, v63, v20, 0
	v_fmac_f32_e32 v70, v62, v24
	v_fma_f32 v71, v63, v21, 0
	v_fmac_f32_e32 v71, v62, v25
	s_waitcnt vmcnt(3)
	v_fma_f32 v72, v63, v10, 0
	s_waitcnt vmcnt(0)
	v_fmac_f32_e32 v72, v62, v14
	v_fma_f32 v73, v63, v11, 0
	v_fmac_f32_e32 v73, v62, v15
	v_fma_f32 v74, v63, v12, 0
	v_fmac_f32_e32 v74, v62, v16
	v_fma_f32 v75, v63, v13, 0
	v_fmac_f32_e32 v75, v62, v17
	v_fma_f32 v76, v63, v2, 0
	v_fmac_f32_e32 v76, v62, v6
	v_fma_f32 v77, v63, v3, 0
	v_fmac_f32_e32 v77, v62, v7
	v_fma_f32 v78, v63, v4, 0
	v_fmac_f32_e32 v78, v62, v8
	v_fma_f32 v79, v63, v5, 0
	v_fmac_f32_e32 v79, v62, v9
	v_mul_f32_e32 v62, 0xbfb8aa3b, v60
	v_exp_f32_e32 v62, v62
	s_waitcnt lgkmcnt(0)
	v_mul_f32_e32 v63, 0xbfb8aa3b, v61
	v_exp_f32_e32 v63, v63
	v_add_f32_e32 v62, 1.0, v62
	v_rcp_f32_e32 v62, v62
	v_add_f32_e32 v63, 1.0, v63
	v_rcp_f32_e32 v63, v63
	v_mul_f32_e32 v60, v60, v62
	v_fma_f32 v80, v18, v60, 0
	v_mul_f32_e32 v61, v61, v63
	v_fmac_f32_e32 v80, v22, v61
	v_fma_f32 v81, v19, v60, 0
	v_fmac_f32_e32 v81, v23, v61
	v_fma_f32 v82, v20, v60, 0
	v_fmac_f32_e32 v82, v24, v61
	ds_bpermute_b32 v83, v1, v68
	ds_bpermute_b32 v84, v1, v69
	ds_bpermute_b32 v85, v1, v70
	ds_bpermute_b32 v86, v1, v71
	ds_bpermute_b32 v87, v1, v72
	ds_bpermute_b32 v88, v1, v73
	ds_bpermute_b32 v89, v1, v74
	ds_bpermute_b32 v90, v1, v75
	ds_bpermute_b32 v91, v1, v76
	ds_bpermute_b32 v92, v1, v77
	ds_bpermute_b32 v93, v1, v78
	ds_bpermute_b32 v94, v1, v79
	ds_bpermute_b32 v95, v1, v80
	ds_bpermute_b32 v96, v1, v81
	ds_bpermute_b32 v97, v1, v82
	s_waitcnt lgkmcnt(14)
	v_add_f32_e32 v68, v68, v83
	s_waitcnt lgkmcnt(13)
	v_add_f32_e32 v69, v69, v84
	s_waitcnt lgkmcnt(12)
	v_add_f32_e32 v70, v70, v85
	s_waitcnt lgkmcnt(11)
	v_add_f32_e32 v71, v71, v86
	s_waitcnt lgkmcnt(10)
	v_add_f32_e32 v72, v72, v87
	s_waitcnt lgkmcnt(9)
	v_add_f32_e32 v73, v73, v88
	s_waitcnt lgkmcnt(8)
	v_add_f32_e32 v74, v74, v89
	s_waitcnt lgkmcnt(7)
	v_add_f32_e32 v75, v75, v90
	s_waitcnt lgkmcnt(6)
	v_add_f32_e32 v76, v76, v91
	s_waitcnt lgkmcnt(5)
	v_add_f32_e32 v77, v77, v92
	s_waitcnt lgkmcnt(4)
	v_add_f32_e32 v78, v78, v93
	s_waitcnt lgkmcnt(3)
	v_add_f32_e32 v79, v79, v94
	s_waitcnt lgkmcnt(2)
	v_add_f32_e32 v80, v80, v95
	s_waitcnt lgkmcnt(1)
	v_add_f32_e32 v81, v81, v96
	s_waitcnt lgkmcnt(0)
	v_add_f32_e32 v82, v82, v97
	ds_bpermute_b32 v83, v46, v68
	ds_bpermute_b32 v84, v46, v69
	ds_bpermute_b32 v85, v46, v70
	ds_bpermute_b32 v86, v46, v71
	ds_bpermute_b32 v87, v46, v72
	ds_bpermute_b32 v88, v46, v73
	ds_bpermute_b32 v89, v46, v74
	ds_bpermute_b32 v90, v46, v75
	ds_bpermute_b32 v91, v46, v76
	ds_bpermute_b32 v92, v46, v77
	ds_bpermute_b32 v93, v46, v78
	ds_bpermute_b32 v94, v46, v79
	ds_bpermute_b32 v95, v46, v80
	ds_bpermute_b32 v96, v46, v81
	ds_bpermute_b32 v97, v46, v82
	s_waitcnt lgkmcnt(14)
	v_add_f32_e32 v68, v68, v83
	s_waitcnt lgkmcnt(13)
	v_add_f32_e32 v69, v69, v84
	s_waitcnt lgkmcnt(12)
	v_add_f32_e32 v70, v70, v85
	s_waitcnt lgkmcnt(11)
	v_add_f32_e32 v71, v71, v86
	s_waitcnt lgkmcnt(10)
	v_add_f32_e32 v72, v72, v87
	s_waitcnt lgkmcnt(9)
	v_add_f32_e32 v73, v73, v88
	s_waitcnt lgkmcnt(8)
	v_add_f32_e32 v74, v74, v89
	s_waitcnt lgkmcnt(7)
	v_add_f32_e32 v75, v75, v90
	s_waitcnt lgkmcnt(6)
	v_add_f32_e32 v76, v76, v91
	s_waitcnt lgkmcnt(5)
	v_add_f32_e32 v77, v77, v92
	s_waitcnt lgkmcnt(4)
	v_add_f32_e32 v78, v78, v93
	s_waitcnt lgkmcnt(3)
	v_add_f32_e32 v79, v79, v94
	s_waitcnt lgkmcnt(2)
	v_add_f32_e32 v80, v80, v95
	s_waitcnt lgkmcnt(1)
	v_add_f32_e32 v81, v81, v96
	s_waitcnt lgkmcnt(0)
	v_add_f32_e32 v82, v82, v97
	ds_bpermute_b32 v83, v47, v68
	ds_bpermute_b32 v84, v47, v69
	ds_bpermute_b32 v85, v47, v70
	ds_bpermute_b32 v86, v47, v71
	ds_bpermute_b32 v87, v47, v72
	ds_bpermute_b32 v88, v47, v73
	ds_bpermute_b32 v89, v47, v74
	ds_bpermute_b32 v90, v47, v75
	ds_bpermute_b32 v91, v47, v76
	ds_bpermute_b32 v92, v47, v77
	ds_bpermute_b32 v93, v47, v78
	ds_bpermute_b32 v94, v47, v79
	ds_bpermute_b32 v95, v47, v80
	ds_bpermute_b32 v96, v47, v81
	ds_bpermute_b32 v97, v47, v82
	s_waitcnt lgkmcnt(14)
	v_add_f32_e32 v68, v68, v83
	s_waitcnt lgkmcnt(13)
	v_add_f32_e32 v69, v69, v84
	s_waitcnt lgkmcnt(12)
	v_add_f32_e32 v70, v70, v85
	s_waitcnt lgkmcnt(11)
	v_add_f32_e32 v71, v71, v86
	s_waitcnt lgkmcnt(10)
	v_add_f32_e32 v72, v72, v87
	s_waitcnt lgkmcnt(9)
	v_add_f32_e32 v73, v73, v88
	s_waitcnt lgkmcnt(8)
	v_add_f32_e32 v74, v74, v89
	s_waitcnt lgkmcnt(7)
	v_add_f32_e32 v75, v75, v90
	s_waitcnt lgkmcnt(6)
	v_add_f32_e32 v76, v76, v91
	s_waitcnt lgkmcnt(5)
	v_add_f32_e32 v77, v77, v92
	s_waitcnt lgkmcnt(4)
	v_add_f32_e32 v78, v78, v93
	s_waitcnt lgkmcnt(3)
	v_add_f32_e32 v79, v79, v94
	s_waitcnt lgkmcnt(2)
	v_add_f32_e32 v80, v80, v95
	s_waitcnt lgkmcnt(1)
	v_add_f32_e32 v81, v81, v96
	s_waitcnt lgkmcnt(0)
	v_add_f32_e32 v82, v82, v97
	ds_bpermute_b32 v83, v48, v68
	ds_bpermute_b32 v84, v48, v69
	ds_bpermute_b32 v85, v48, v70
	ds_bpermute_b32 v86, v48, v71
	ds_bpermute_b32 v87, v48, v72
	ds_bpermute_b32 v88, v48, v73
	ds_bpermute_b32 v89, v48, v74
	ds_bpermute_b32 v90, v48, v75
	ds_bpermute_b32 v91, v48, v76
	ds_bpermute_b32 v92, v48, v77
	ds_bpermute_b32 v93, v48, v78
	ds_bpermute_b32 v94, v48, v79
	ds_bpermute_b32 v95, v48, v80
	ds_bpermute_b32 v96, v48, v81
	ds_bpermute_b32 v97, v48, v82
	s_waitcnt lgkmcnt(14)
	v_add_f32_e32 v68, v68, v83
	s_waitcnt lgkmcnt(13)
	v_add_f32_e32 v69, v69, v84
	s_waitcnt lgkmcnt(12)
	v_add_f32_e32 v70, v70, v85
	s_waitcnt lgkmcnt(11)
	v_add_f32_e32 v71, v71, v86
	s_waitcnt lgkmcnt(10)
	v_add_f32_e32 v72, v72, v87
	s_waitcnt lgkmcnt(9)
	v_add_f32_e32 v73, v73, v88
	s_waitcnt lgkmcnt(8)
	v_add_f32_e32 v74, v74, v89
	s_waitcnt lgkmcnt(7)
	v_add_f32_e32 v75, v75, v90
	s_waitcnt lgkmcnt(6)
	v_add_f32_e32 v76, v76, v91
	s_waitcnt lgkmcnt(5)
	v_add_f32_e32 v77, v77, v92
	s_waitcnt lgkmcnt(4)
	v_add_f32_e32 v78, v78, v93
	s_waitcnt lgkmcnt(3)
	v_add_f32_e32 v79, v79, v94
	s_waitcnt lgkmcnt(2)
	v_add_f32_e32 v80, v80, v95
	s_waitcnt lgkmcnt(1)
	v_add_f32_e32 v81, v81, v96
	s_waitcnt lgkmcnt(0)
	v_add_f32_e32 v82, v82, v97
	ds_bpermute_b32 v83, v49, v68
	ds_bpermute_b32 v84, v49, v69
	ds_bpermute_b32 v85, v49, v70
	ds_bpermute_b32 v86, v49, v71
	ds_bpermute_b32 v87, v49, v72
	ds_bpermute_b32 v88, v49, v73
	ds_bpermute_b32 v89, v49, v74
	ds_bpermute_b32 v90, v49, v75
	ds_bpermute_b32 v91, v49, v76
	ds_bpermute_b32 v92, v49, v77
	ds_bpermute_b32 v93, v49, v78
	ds_bpermute_b32 v94, v49, v79
	ds_bpermute_b32 v95, v49, v80
	ds_bpermute_b32 v96, v49, v81
	ds_bpermute_b32 v97, v49, v82
	s_waitcnt lgkmcnt(14)
	v_add_f32_e32 v68, v68, v83
	s_waitcnt lgkmcnt(13)
	v_add_f32_e32 v69, v69, v84
	s_waitcnt lgkmcnt(12)
	v_add_f32_e32 v70, v70, v85
	s_waitcnt lgkmcnt(11)
	v_add_f32_e32 v71, v71, v86
	s_waitcnt lgkmcnt(10)
	v_add_f32_e32 v72, v72, v87
	s_waitcnt lgkmcnt(9)
	v_add_f32_e32 v73, v73, v88
	s_waitcnt lgkmcnt(8)
	v_add_f32_e32 v74, v74, v89
	s_waitcnt lgkmcnt(7)
	v_add_f32_e32 v75, v75, v90
	s_waitcnt lgkmcnt(6)
	v_add_f32_e32 v76, v76, v91
	s_waitcnt lgkmcnt(5)
	v_add_f32_e32 v77, v77, v92
	s_waitcnt lgkmcnt(4)
	v_add_f32_e32 v78, v78, v93
	s_waitcnt lgkmcnt(3)
	v_add_f32_e32 v79, v79, v94
	s_waitcnt lgkmcnt(2)
	v_add_f32_e32 v80, v80, v95
	s_waitcnt lgkmcnt(1)
	v_add_f32_e32 v81, v81, v96
	s_waitcnt lgkmcnt(0)
	v_add_f32_e32 v82, v82, v97
	ds_bpermute_b32 v83, v50, v68
	ds_bpermute_b32 v84, v50, v69
	ds_bpermute_b32 v85, v50, v70
	ds_bpermute_b32 v86, v50, v71
	ds_bpermute_b32 v87, v50, v72
	ds_bpermute_b32 v88, v50, v73
	ds_bpermute_b32 v89, v50, v74
	ds_bpermute_b32 v90, v50, v75
	ds_bpermute_b32 v91, v50, v76
	ds_bpermute_b32 v92, v50, v77
	ds_bpermute_b32 v93, v50, v78
	ds_bpermute_b32 v94, v50, v79
	ds_bpermute_b32 v95, v50, v80
	ds_bpermute_b32 v96, v50, v81
	ds_bpermute_b32 v97, v50, v82
	s_waitcnt lgkmcnt(14)
	v_add_f32_e32 v68, v68, v83
	s_waitcnt lgkmcnt(13)
	v_add_f32_e32 v69, v69, v84
	s_waitcnt lgkmcnt(12)
	v_add_f32_e32 v70, v70, v85
	s_waitcnt lgkmcnt(11)
	v_add_f32_e32 v71, v71, v86
	s_waitcnt lgkmcnt(10)
	v_add_f32_e32 v72, v72, v87
	s_waitcnt lgkmcnt(9)
	v_add_f32_e32 v73, v73, v88
	s_waitcnt lgkmcnt(8)
	v_add_f32_e32 v74, v74, v89
	s_waitcnt lgkmcnt(7)
	v_add_f32_e32 v75, v75, v90
	s_waitcnt lgkmcnt(6)
	v_add_f32_e32 v76, v76, v91
	s_waitcnt lgkmcnt(5)
	v_add_f32_e32 v77, v77, v92
	s_waitcnt lgkmcnt(4)
	v_add_f32_e32 v78, v78, v93
	s_waitcnt lgkmcnt(3)
	v_add_f32_e32 v79, v79, v94
	s_waitcnt lgkmcnt(2)
	v_add_f32_e32 v80, v80, v95
	s_waitcnt lgkmcnt(1)
	v_add_f32_e32 v81, v81, v96
	s_waitcnt lgkmcnt(0)
	v_add_f32_e32 v82, v82, v97
	s_and_saveexec_b64 s[12:13], vcc
	v_mov_b32_e32 v98, s2
	ds_write_b32 v98, v68
	ds_write_b32 v98, v69 offset:4
	ds_write_b32 v98, v70 offset:8
	ds_write_b32 v98, v71 offset:12
	ds_write_b32 v98, v72 offset:16
	ds_write_b32 v98, v73 offset:20
	ds_write_b32 v98, v74 offset:24
	ds_write_b32 v98, v75 offset:28
	ds_write_b32 v98, v76 offset:32
	ds_write_b32 v98, v77 offset:36
	ds_write_b32 v98, v78 offset:40
	ds_write_b32 v98, v79 offset:44
	ds_write_b32 v98, v80 offset:48
	ds_write_b32 v98, v81 offset:52
	ds_write_b32 v98, v82 offset:56
	s_or_b64 exec, exec, s[12:13]
	v_fma_f32 v68, v21, v60, 0
	v_fmac_f32_e32 v68, v25, v61
	v_fma_f32 v69, v60, v10, 0
	v_fmac_f32_e32 v69, v61, v14
	v_fma_f32 v70, v60, v11, 0
	v_fmac_f32_e32 v70, v61, v15
	v_fma_f32 v71, v60, v12, 0
	v_fmac_f32_e32 v71, v61, v16
	v_fma_f32 v72, v60, v13, 0
	v_fmac_f32_e32 v72, v61, v17
	v_fma_f32 v73, v60, v2, 0
	v_fmac_f32_e32 v73, v61, v6
	v_fma_f32 v74, v60, v3, 0
	v_fmac_f32_e32 v74, v61, v7
	v_fma_f32 v75, v60, v4, 0
	v_fmac_f32_e32 v75, v61, v8
	v_fma_f32 v76, v60, v5, 0
	v_fmac_f32_e32 v76, v61, v9
	v_mul_f32_e32 v60, 0xbfb8aa3b, v58
	v_exp_f32_e32 v60, v60
	s_waitcnt lgkmcnt(0)
	v_mul_f32_e32 v61, 0xbfb8aa3b, v59
	v_exp_f32_e32 v61, v61
	v_add_f32_e32 v60, 1.0, v60
	v_rcp_f32_e32 v60, v60
	v_add_f32_e32 v61, 1.0, v61
	v_rcp_f32_e32 v61, v61
	v_mul_f32_e32 v58, v58, v60
	v_fma_f32 v77, v18, v58, 0
	v_mul_f32_e32 v59, v59, v61
	v_fmac_f32_e32 v77, v22, v59
	v_fma_f32 v78, v19, v58, 0
	v_fmac_f32_e32 v78, v23, v59
	v_fma_f32 v79, v20, v58, 0
	v_fmac_f32_e32 v79, v24, v59
	v_fma_f32 v80, v21, v58, 0
	v_fmac_f32_e32 v80, v25, v59
	v_fma_f32 v81, v10, v58, 0
	v_fmac_f32_e32 v81, v14, v59
	v_fma_f32 v82, v11, v58, 0
	v_fmac_f32_e32 v82, v15, v59
	ds_bpermute_b32 v83, v1, v68
	ds_bpermute_b32 v84, v1, v69
	ds_bpermute_b32 v85, v1, v70
	ds_bpermute_b32 v86, v1, v71
	ds_bpermute_b32 v87, v1, v72
	ds_bpermute_b32 v88, v1, v73
	ds_bpermute_b32 v89, v1, v74
	ds_bpermute_b32 v90, v1, v75
	ds_bpermute_b32 v91, v1, v76
	ds_bpermute_b32 v92, v1, v77
	ds_bpermute_b32 v93, v1, v78
	ds_bpermute_b32 v94, v1, v79
	ds_bpermute_b32 v95, v1, v80
	ds_bpermute_b32 v96, v1, v81
	ds_bpermute_b32 v97, v1, v82
	s_waitcnt lgkmcnt(14)
	v_add_f32_e32 v68, v68, v83
	s_waitcnt lgkmcnt(13)
	v_add_f32_e32 v69, v69, v84
	s_waitcnt lgkmcnt(12)
	v_add_f32_e32 v70, v70, v85
	s_waitcnt lgkmcnt(11)
	v_add_f32_e32 v71, v71, v86
	s_waitcnt lgkmcnt(10)
	v_add_f32_e32 v72, v72, v87
	s_waitcnt lgkmcnt(9)
	v_add_f32_e32 v73, v73, v88
	s_waitcnt lgkmcnt(8)
	v_add_f32_e32 v74, v74, v89
	s_waitcnt lgkmcnt(7)
	v_add_f32_e32 v75, v75, v90
	s_waitcnt lgkmcnt(6)
	v_add_f32_e32 v76, v76, v91
	s_waitcnt lgkmcnt(5)
	v_add_f32_e32 v77, v77, v92
	s_waitcnt lgkmcnt(4)
	v_add_f32_e32 v78, v78, v93
	s_waitcnt lgkmcnt(3)
	v_add_f32_e32 v79, v79, v94
	s_waitcnt lgkmcnt(2)
	v_add_f32_e32 v80, v80, v95
	s_waitcnt lgkmcnt(1)
	v_add_f32_e32 v81, v81, v96
	s_waitcnt lgkmcnt(0)
	v_add_f32_e32 v82, v82, v97
	ds_bpermute_b32 v83, v46, v68
	ds_bpermute_b32 v84, v46, v69
	ds_bpermute_b32 v85, v46, v70
	ds_bpermute_b32 v86, v46, v71
	ds_bpermute_b32 v87, v46, v72
	ds_bpermute_b32 v88, v46, v73
	ds_bpermute_b32 v89, v46, v74
	ds_bpermute_b32 v90, v46, v75
	ds_bpermute_b32 v91, v46, v76
	ds_bpermute_b32 v92, v46, v77
	ds_bpermute_b32 v93, v46, v78
	ds_bpermute_b32 v94, v46, v79
	ds_bpermute_b32 v95, v46, v80
	ds_bpermute_b32 v96, v46, v81
	ds_bpermute_b32 v97, v46, v82
	s_waitcnt lgkmcnt(14)
	v_add_f32_e32 v68, v68, v83
	s_waitcnt lgkmcnt(13)
	v_add_f32_e32 v69, v69, v84
	s_waitcnt lgkmcnt(12)
	v_add_f32_e32 v70, v70, v85
	s_waitcnt lgkmcnt(11)
	v_add_f32_e32 v71, v71, v86
	s_waitcnt lgkmcnt(10)
	v_add_f32_e32 v72, v72, v87
	s_waitcnt lgkmcnt(9)
	v_add_f32_e32 v73, v73, v88
	s_waitcnt lgkmcnt(8)
	v_add_f32_e32 v74, v74, v89
	s_waitcnt lgkmcnt(7)
	v_add_f32_e32 v75, v75, v90
	s_waitcnt lgkmcnt(6)
	v_add_f32_e32 v76, v76, v91
	s_waitcnt lgkmcnt(5)
	v_add_f32_e32 v77, v77, v92
	s_waitcnt lgkmcnt(4)
	v_add_f32_e32 v78, v78, v93
	s_waitcnt lgkmcnt(3)
	v_add_f32_e32 v79, v79, v94
	s_waitcnt lgkmcnt(2)
	v_add_f32_e32 v80, v80, v95
	s_waitcnt lgkmcnt(1)
	v_add_f32_e32 v81, v81, v96
	s_waitcnt lgkmcnt(0)
	v_add_f32_e32 v82, v82, v97
	ds_bpermute_b32 v83, v47, v68
	ds_bpermute_b32 v84, v47, v69
	ds_bpermute_b32 v85, v47, v70
	ds_bpermute_b32 v86, v47, v71
	ds_bpermute_b32 v87, v47, v72
	ds_bpermute_b32 v88, v47, v73
	ds_bpermute_b32 v89, v47, v74
	ds_bpermute_b32 v90, v47, v75
	ds_bpermute_b32 v91, v47, v76
	ds_bpermute_b32 v92, v47, v77
	ds_bpermute_b32 v93, v47, v78
	ds_bpermute_b32 v94, v47, v79
	ds_bpermute_b32 v95, v47, v80
	ds_bpermute_b32 v96, v47, v81
	ds_bpermute_b32 v97, v47, v82
	s_waitcnt lgkmcnt(14)
	v_add_f32_e32 v68, v68, v83
	s_waitcnt lgkmcnt(13)
	v_add_f32_e32 v69, v69, v84
	s_waitcnt lgkmcnt(12)
	v_add_f32_e32 v70, v70, v85
	s_waitcnt lgkmcnt(11)
	v_add_f32_e32 v71, v71, v86
	s_waitcnt lgkmcnt(10)
	v_add_f32_e32 v72, v72, v87
	s_waitcnt lgkmcnt(9)
	v_add_f32_e32 v73, v73, v88
	s_waitcnt lgkmcnt(8)
	v_add_f32_e32 v74, v74, v89
	s_waitcnt lgkmcnt(7)
	v_add_f32_e32 v75, v75, v90
	s_waitcnt lgkmcnt(6)
	v_add_f32_e32 v76, v76, v91
	s_waitcnt lgkmcnt(5)
	v_add_f32_e32 v77, v77, v92
	s_waitcnt lgkmcnt(4)
	v_add_f32_e32 v78, v78, v93
	s_waitcnt lgkmcnt(3)
	v_add_f32_e32 v79, v79, v94
	s_waitcnt lgkmcnt(2)
	v_add_f32_e32 v80, v80, v95
	s_waitcnt lgkmcnt(1)
	v_add_f32_e32 v81, v81, v96
	s_waitcnt lgkmcnt(0)
	v_add_f32_e32 v82, v82, v97
	ds_bpermute_b32 v83, v48, v68
	ds_bpermute_b32 v84, v48, v69
	ds_bpermute_b32 v85, v48, v70
	ds_bpermute_b32 v86, v48, v71
	ds_bpermute_b32 v87, v48, v72
	ds_bpermute_b32 v88, v48, v73
	ds_bpermute_b32 v89, v48, v74
	ds_bpermute_b32 v90, v48, v75
	ds_bpermute_b32 v91, v48, v76
	ds_bpermute_b32 v92, v48, v77
	ds_bpermute_b32 v93, v48, v78
	ds_bpermute_b32 v94, v48, v79
	ds_bpermute_b32 v95, v48, v80
	ds_bpermute_b32 v96, v48, v81
	ds_bpermute_b32 v97, v48, v82
	s_waitcnt lgkmcnt(14)
	v_add_f32_e32 v68, v68, v83
	s_waitcnt lgkmcnt(13)
	v_add_f32_e32 v69, v69, v84
	s_waitcnt lgkmcnt(12)
	v_add_f32_e32 v70, v70, v85
	s_waitcnt lgkmcnt(11)
	v_add_f32_e32 v71, v71, v86
	s_waitcnt lgkmcnt(10)
	v_add_f32_e32 v72, v72, v87
	s_waitcnt lgkmcnt(9)
	v_add_f32_e32 v73, v73, v88
	s_waitcnt lgkmcnt(8)
	v_add_f32_e32 v74, v74, v89
	s_waitcnt lgkmcnt(7)
	v_add_f32_e32 v75, v75, v90
	s_waitcnt lgkmcnt(6)
	v_add_f32_e32 v76, v76, v91
	s_waitcnt lgkmcnt(5)
	v_add_f32_e32 v77, v77, v92
	s_waitcnt lgkmcnt(4)
	v_add_f32_e32 v78, v78, v93
	s_waitcnt lgkmcnt(3)
	v_add_f32_e32 v79, v79, v94
	s_waitcnt lgkmcnt(2)
	v_add_f32_e32 v80, v80, v95
	s_waitcnt lgkmcnt(1)
	v_add_f32_e32 v81, v81, v96
	s_waitcnt lgkmcnt(0)
	v_add_f32_e32 v82, v82, v97
	ds_bpermute_b32 v83, v49, v68
	ds_bpermute_b32 v84, v49, v69
	ds_bpermute_b32 v85, v49, v70
	ds_bpermute_b32 v86, v49, v71
	ds_bpermute_b32 v87, v49, v72
	ds_bpermute_b32 v88, v49, v73
	ds_bpermute_b32 v89, v49, v74
	ds_bpermute_b32 v90, v49, v75
	ds_bpermute_b32 v91, v49, v76
	ds_bpermute_b32 v92, v49, v77
	ds_bpermute_b32 v93, v49, v78
	ds_bpermute_b32 v94, v49, v79
	ds_bpermute_b32 v95, v49, v80
	ds_bpermute_b32 v96, v49, v81
	ds_bpermute_b32 v97, v49, v82
	s_waitcnt lgkmcnt(14)
	v_add_f32_e32 v68, v68, v83
	s_waitcnt lgkmcnt(13)
	v_add_f32_e32 v69, v69, v84
	s_waitcnt lgkmcnt(12)
	v_add_f32_e32 v70, v70, v85
	s_waitcnt lgkmcnt(11)
	v_add_f32_e32 v71, v71, v86
	s_waitcnt lgkmcnt(10)
	v_add_f32_e32 v72, v72, v87
	s_waitcnt lgkmcnt(9)
	v_add_f32_e32 v73, v73, v88
	s_waitcnt lgkmcnt(8)
	v_add_f32_e32 v74, v74, v89
	s_waitcnt lgkmcnt(7)
	v_add_f32_e32 v75, v75, v90
	s_waitcnt lgkmcnt(6)
	v_add_f32_e32 v76, v76, v91
	s_waitcnt lgkmcnt(5)
	v_add_f32_e32 v77, v77, v92
	s_waitcnt lgkmcnt(4)
	v_add_f32_e32 v78, v78, v93
	s_waitcnt lgkmcnt(3)
	v_add_f32_e32 v79, v79, v94
	s_waitcnt lgkmcnt(2)
	v_add_f32_e32 v80, v80, v95
	s_waitcnt lgkmcnt(1)
	v_add_f32_e32 v81, v81, v96
	s_waitcnt lgkmcnt(0)
	v_add_f32_e32 v82, v82, v97
	ds_bpermute_b32 v83, v50, v68
	ds_bpermute_b32 v84, v50, v69
	ds_bpermute_b32 v85, v50, v70
	ds_bpermute_b32 v86, v50, v71
	ds_bpermute_b32 v87, v50, v72
	ds_bpermute_b32 v88, v50, v73
	ds_bpermute_b32 v89, v50, v74
	ds_bpermute_b32 v90, v50, v75
	ds_bpermute_b32 v91, v50, v76
	ds_bpermute_b32 v92, v50, v77
	ds_bpermute_b32 v93, v50, v78
	ds_bpermute_b32 v94, v50, v79
	ds_bpermute_b32 v95, v50, v80
	ds_bpermute_b32 v96, v50, v81
	ds_bpermute_b32 v97, v50, v82
	s_waitcnt lgkmcnt(14)
	v_add_f32_e32 v68, v68, v83
	s_waitcnt lgkmcnt(13)
	v_add_f32_e32 v69, v69, v84
	s_waitcnt lgkmcnt(12)
	v_add_f32_e32 v70, v70, v85
	s_waitcnt lgkmcnt(11)
	v_add_f32_e32 v71, v71, v86
	s_waitcnt lgkmcnt(10)
	v_add_f32_e32 v72, v72, v87
	s_waitcnt lgkmcnt(9)
	v_add_f32_e32 v73, v73, v88
	s_waitcnt lgkmcnt(8)
	v_add_f32_e32 v74, v74, v89
	s_waitcnt lgkmcnt(7)
	v_add_f32_e32 v75, v75, v90
	s_waitcnt lgkmcnt(6)
	v_add_f32_e32 v76, v76, v91
	s_waitcnt lgkmcnt(5)
	v_add_f32_e32 v77, v77, v92
	s_waitcnt lgkmcnt(4)
	v_add_f32_e32 v78, v78, v93
	s_waitcnt lgkmcnt(3)
	v_add_f32_e32 v79, v79, v94
	s_waitcnt lgkmcnt(2)
	v_add_f32_e32 v80, v80, v95
	s_waitcnt lgkmcnt(1)
	v_add_f32_e32 v81, v81, v96
	s_waitcnt lgkmcnt(0)
	v_add_f32_e32 v82, v82, v97
	s_and_saveexec_b64 s[12:13], vcc
	v_mov_b32_e32 v98, s2
	ds_write_b32 v98, v68 offset:60
	ds_write_b32 v98, v69 offset:64
	ds_write_b32 v98, v70 offset:68
	ds_write_b32 v98, v71 offset:72
	ds_write_b32 v98, v72 offset:76
	ds_write_b32 v98, v73 offset:80
	ds_write_b32 v98, v74 offset:84
	ds_write_b32 v98, v75 offset:88
	ds_write_b32 v98, v76 offset:92
	ds_write_b32 v98, v77 offset:96
	ds_write_b32 v98, v78 offset:100
	ds_write_b32 v98, v79 offset:104
	ds_write_b32 v98, v80 offset:108
	ds_write_b32 v98, v81 offset:112
	ds_write_b32 v98, v82 offset:116
	s_or_b64 exec, exec, s[12:13]
	v_fma_f32 v68, v12, v58, 0
	v_fmac_f32_e32 v68, v16, v59
	v_fma_f32 v69, v13, v58, 0
	v_fmac_f32_e32 v69, v17, v59
	v_fma_f32 v70, v58, v2, 0
	v_fmac_f32_e32 v70, v59, v6
	v_fma_f32 v71, v58, v3, 0
	v_fmac_f32_e32 v71, v59, v7
	v_fma_f32 v72, v58, v4, 0
	v_fmac_f32_e32 v72, v59, v8
	v_fma_f32 v73, v58, v5, 0
	v_fmac_f32_e32 v73, v59, v9
	v_mul_f32_e32 v58, 0xbfb8aa3b, v56
	v_exp_f32_e32 v58, v58
	s_waitcnt lgkmcnt(0)
	v_mul_f32_e32 v59, 0xbfb8aa3b, v57
	v_exp_f32_e32 v59, v59
	v_add_f32_e32 v58, 1.0, v58
	v_rcp_f32_e32 v58, v58
	v_add_f32_e32 v59, 1.0, v59
	v_rcp_f32_e32 v59, v59
	v_mul_f32_e32 v56, v56, v58
	v_fma_f32 v74, v18, v56, 0
	v_mul_f32_e32 v57, v57, v59
	v_fmac_f32_e32 v74, v22, v57
	v_fma_f32 v75, v19, v56, 0
	v_fmac_f32_e32 v75, v23, v57
	v_fma_f32 v76, v20, v56, 0
	v_fmac_f32_e32 v76, v24, v57
	v_fma_f32 v77, v21, v56, 0
	v_fmac_f32_e32 v77, v25, v57
	v_fma_f32 v78, v10, v56, 0
	v_fmac_f32_e32 v78, v14, v57
	v_fma_f32 v79, v11, v56, 0
	v_fmac_f32_e32 v79, v15, v57
	v_fma_f32 v80, v12, v56, 0
	v_fmac_f32_e32 v80, v16, v57
	v_fma_f32 v81, v13, v56, 0
	v_fmac_f32_e32 v81, v17, v57
	v_fma_f32 v82, v2, v56, 0
	v_fmac_f32_e32 v82, v6, v57
	ds_bpermute_b32 v83, v1, v68
	ds_bpermute_b32 v84, v1, v69
	ds_bpermute_b32 v85, v1, v70
	ds_bpermute_b32 v86, v1, v71
	ds_bpermute_b32 v87, v1, v72
	ds_bpermute_b32 v88, v1, v73
	ds_bpermute_b32 v89, v1, v74
	ds_bpermute_b32 v90, v1, v75
	ds_bpermute_b32 v91, v1, v76
	ds_bpermute_b32 v92, v1, v77
	ds_bpermute_b32 v93, v1, v78
	ds_bpermute_b32 v94, v1, v79
	ds_bpermute_b32 v95, v1, v80
	ds_bpermute_b32 v96, v1, v81
	ds_bpermute_b32 v97, v1, v82
	s_waitcnt lgkmcnt(14)
	v_add_f32_e32 v68, v68, v83
	s_waitcnt lgkmcnt(13)
	v_add_f32_e32 v69, v69, v84
	s_waitcnt lgkmcnt(12)
	v_add_f32_e32 v70, v70, v85
	s_waitcnt lgkmcnt(11)
	v_add_f32_e32 v71, v71, v86
	s_waitcnt lgkmcnt(10)
	v_add_f32_e32 v72, v72, v87
	s_waitcnt lgkmcnt(9)
	v_add_f32_e32 v73, v73, v88
	s_waitcnt lgkmcnt(8)
	v_add_f32_e32 v74, v74, v89
	s_waitcnt lgkmcnt(7)
	v_add_f32_e32 v75, v75, v90
	s_waitcnt lgkmcnt(6)
	v_add_f32_e32 v76, v76, v91
	s_waitcnt lgkmcnt(5)
	v_add_f32_e32 v77, v77, v92
	s_waitcnt lgkmcnt(4)
	v_add_f32_e32 v78, v78, v93
	s_waitcnt lgkmcnt(3)
	v_add_f32_e32 v79, v79, v94
	s_waitcnt lgkmcnt(2)
	v_add_f32_e32 v80, v80, v95
	s_waitcnt lgkmcnt(1)
	v_add_f32_e32 v81, v81, v96
	s_waitcnt lgkmcnt(0)
	v_add_f32_e32 v82, v82, v97
	ds_bpermute_b32 v83, v46, v68
	ds_bpermute_b32 v84, v46, v69
	ds_bpermute_b32 v85, v46, v70
	ds_bpermute_b32 v86, v46, v71
	ds_bpermute_b32 v87, v46, v72
	ds_bpermute_b32 v88, v46, v73
	ds_bpermute_b32 v89, v46, v74
	ds_bpermute_b32 v90, v46, v75
	ds_bpermute_b32 v91, v46, v76
	ds_bpermute_b32 v92, v46, v77
	ds_bpermute_b32 v93, v46, v78
	ds_bpermute_b32 v94, v46, v79
	ds_bpermute_b32 v95, v46, v80
	ds_bpermute_b32 v96, v46, v81
	ds_bpermute_b32 v97, v46, v82
	s_waitcnt lgkmcnt(14)
	v_add_f32_e32 v68, v68, v83
	s_waitcnt lgkmcnt(13)
	v_add_f32_e32 v69, v69, v84
	s_waitcnt lgkmcnt(12)
	v_add_f32_e32 v70, v70, v85
	s_waitcnt lgkmcnt(11)
	v_add_f32_e32 v71, v71, v86
	s_waitcnt lgkmcnt(10)
	v_add_f32_e32 v72, v72, v87
	s_waitcnt lgkmcnt(9)
	v_add_f32_e32 v73, v73, v88
	s_waitcnt lgkmcnt(8)
	v_add_f32_e32 v74, v74, v89
	s_waitcnt lgkmcnt(7)
	v_add_f32_e32 v75, v75, v90
	s_waitcnt lgkmcnt(6)
	v_add_f32_e32 v76, v76, v91
	s_waitcnt lgkmcnt(5)
	v_add_f32_e32 v77, v77, v92
	s_waitcnt lgkmcnt(4)
	v_add_f32_e32 v78, v78, v93
	s_waitcnt lgkmcnt(3)
	v_add_f32_e32 v79, v79, v94
	s_waitcnt lgkmcnt(2)
	v_add_f32_e32 v80, v80, v95
	s_waitcnt lgkmcnt(1)
	v_add_f32_e32 v81, v81, v96
	s_waitcnt lgkmcnt(0)
	v_add_f32_e32 v82, v82, v97
	ds_bpermute_b32 v83, v47, v68
	ds_bpermute_b32 v84, v47, v69
	ds_bpermute_b32 v85, v47, v70
	ds_bpermute_b32 v86, v47, v71
	ds_bpermute_b32 v87, v47, v72
	ds_bpermute_b32 v88, v47, v73
	ds_bpermute_b32 v89, v47, v74
	ds_bpermute_b32 v90, v47, v75
	ds_bpermute_b32 v91, v47, v76
	ds_bpermute_b32 v92, v47, v77
	ds_bpermute_b32 v93, v47, v78
	ds_bpermute_b32 v94, v47, v79
	ds_bpermute_b32 v95, v47, v80
	ds_bpermute_b32 v96, v47, v81
	ds_bpermute_b32 v97, v47, v82
	s_waitcnt lgkmcnt(14)
	v_add_f32_e32 v68, v68, v83
	s_waitcnt lgkmcnt(13)
	v_add_f32_e32 v69, v69, v84
	s_waitcnt lgkmcnt(12)
	v_add_f32_e32 v70, v70, v85
	s_waitcnt lgkmcnt(11)
	v_add_f32_e32 v71, v71, v86
	s_waitcnt lgkmcnt(10)
	v_add_f32_e32 v72, v72, v87
	s_waitcnt lgkmcnt(9)
	v_add_f32_e32 v73, v73, v88
	s_waitcnt lgkmcnt(8)
	v_add_f32_e32 v74, v74, v89
	s_waitcnt lgkmcnt(7)
	v_add_f32_e32 v75, v75, v90
	s_waitcnt lgkmcnt(6)
	v_add_f32_e32 v76, v76, v91
	s_waitcnt lgkmcnt(5)
	v_add_f32_e32 v77, v77, v92
	s_waitcnt lgkmcnt(4)
	v_add_f32_e32 v78, v78, v93
	s_waitcnt lgkmcnt(3)
	v_add_f32_e32 v79, v79, v94
	s_waitcnt lgkmcnt(2)
	v_add_f32_e32 v80, v80, v95
	s_waitcnt lgkmcnt(1)
	v_add_f32_e32 v81, v81, v96
	s_waitcnt lgkmcnt(0)
	v_add_f32_e32 v82, v82, v97
	ds_bpermute_b32 v83, v48, v68
	ds_bpermute_b32 v84, v48, v69
	ds_bpermute_b32 v85, v48, v70
	ds_bpermute_b32 v86, v48, v71
	ds_bpermute_b32 v87, v48, v72
	ds_bpermute_b32 v88, v48, v73
	ds_bpermute_b32 v89, v48, v74
	ds_bpermute_b32 v90, v48, v75
	ds_bpermute_b32 v91, v48, v76
	ds_bpermute_b32 v92, v48, v77
	ds_bpermute_b32 v93, v48, v78
	ds_bpermute_b32 v94, v48, v79
	ds_bpermute_b32 v95, v48, v80
	ds_bpermute_b32 v96, v48, v81
	ds_bpermute_b32 v97, v48, v82
	s_waitcnt lgkmcnt(14)
	v_add_f32_e32 v68, v68, v83
	s_waitcnt lgkmcnt(13)
	v_add_f32_e32 v69, v69, v84
	s_waitcnt lgkmcnt(12)
	v_add_f32_e32 v70, v70, v85
	s_waitcnt lgkmcnt(11)
	v_add_f32_e32 v71, v71, v86
	s_waitcnt lgkmcnt(10)
	v_add_f32_e32 v72, v72, v87
	s_waitcnt lgkmcnt(9)
	v_add_f32_e32 v73, v73, v88
	s_waitcnt lgkmcnt(8)
	v_add_f32_e32 v74, v74, v89
	s_waitcnt lgkmcnt(7)
	v_add_f32_e32 v75, v75, v90
	s_waitcnt lgkmcnt(6)
	v_add_f32_e32 v76, v76, v91
	s_waitcnt lgkmcnt(5)
	v_add_f32_e32 v77, v77, v92
	s_waitcnt lgkmcnt(4)
	v_add_f32_e32 v78, v78, v93
	s_waitcnt lgkmcnt(3)
	v_add_f32_e32 v79, v79, v94
	s_waitcnt lgkmcnt(2)
	v_add_f32_e32 v80, v80, v95
	s_waitcnt lgkmcnt(1)
	v_add_f32_e32 v81, v81, v96
	s_waitcnt lgkmcnt(0)
	v_add_f32_e32 v82, v82, v97
	ds_bpermute_b32 v83, v49, v68
	ds_bpermute_b32 v84, v49, v69
	ds_bpermute_b32 v85, v49, v70
	ds_bpermute_b32 v86, v49, v71
	ds_bpermute_b32 v87, v49, v72
	ds_bpermute_b32 v88, v49, v73
	ds_bpermute_b32 v89, v49, v74
	ds_bpermute_b32 v90, v49, v75
	ds_bpermute_b32 v91, v49, v76
	ds_bpermute_b32 v92, v49, v77
	ds_bpermute_b32 v93, v49, v78
	ds_bpermute_b32 v94, v49, v79
	ds_bpermute_b32 v95, v49, v80
	ds_bpermute_b32 v96, v49, v81
	ds_bpermute_b32 v97, v49, v82
	s_waitcnt lgkmcnt(14)
	v_add_f32_e32 v68, v68, v83
	s_waitcnt lgkmcnt(13)
	v_add_f32_e32 v69, v69, v84
	s_waitcnt lgkmcnt(12)
	v_add_f32_e32 v70, v70, v85
	s_waitcnt lgkmcnt(11)
	v_add_f32_e32 v71, v71, v86
	s_waitcnt lgkmcnt(10)
	v_add_f32_e32 v72, v72, v87
	s_waitcnt lgkmcnt(9)
	v_add_f32_e32 v73, v73, v88
	s_waitcnt lgkmcnt(8)
	v_add_f32_e32 v74, v74, v89
	s_waitcnt lgkmcnt(7)
	v_add_f32_e32 v75, v75, v90
	s_waitcnt lgkmcnt(6)
	v_add_f32_e32 v76, v76, v91
	s_waitcnt lgkmcnt(5)
	v_add_f32_e32 v77, v77, v92
	s_waitcnt lgkmcnt(4)
	v_add_f32_e32 v78, v78, v93
	s_waitcnt lgkmcnt(3)
	v_add_f32_e32 v79, v79, v94
	s_waitcnt lgkmcnt(2)
	v_add_f32_e32 v80, v80, v95
	s_waitcnt lgkmcnt(1)
	v_add_f32_e32 v81, v81, v96
	s_waitcnt lgkmcnt(0)
	v_add_f32_e32 v82, v82, v97
	ds_bpermute_b32 v83, v50, v68
	ds_bpermute_b32 v84, v50, v69
	ds_bpermute_b32 v85, v50, v70
	ds_bpermute_b32 v86, v50, v71
	ds_bpermute_b32 v87, v50, v72
	ds_bpermute_b32 v88, v50, v73
	ds_bpermute_b32 v89, v50, v74
	ds_bpermute_b32 v90, v50, v75
	ds_bpermute_b32 v91, v50, v76
	ds_bpermute_b32 v92, v50, v77
	ds_bpermute_b32 v93, v50, v78
	ds_bpermute_b32 v94, v50, v79
	ds_bpermute_b32 v95, v50, v80
	ds_bpermute_b32 v96, v50, v81
	ds_bpermute_b32 v97, v50, v82
	s_waitcnt lgkmcnt(14)
	v_add_f32_e32 v68, v68, v83
	s_waitcnt lgkmcnt(13)
	v_add_f32_e32 v69, v69, v84
	s_waitcnt lgkmcnt(12)
	v_add_f32_e32 v70, v70, v85
	s_waitcnt lgkmcnt(11)
	v_add_f32_e32 v71, v71, v86
	s_waitcnt lgkmcnt(10)
	v_add_f32_e32 v72, v72, v87
	s_waitcnt lgkmcnt(9)
	v_add_f32_e32 v73, v73, v88
	s_waitcnt lgkmcnt(8)
	v_add_f32_e32 v74, v74, v89
	s_waitcnt lgkmcnt(7)
	v_add_f32_e32 v75, v75, v90
	s_waitcnt lgkmcnt(6)
	v_add_f32_e32 v76, v76, v91
	s_waitcnt lgkmcnt(5)
	v_add_f32_e32 v77, v77, v92
	s_waitcnt lgkmcnt(4)
	v_add_f32_e32 v78, v78, v93
	s_waitcnt lgkmcnt(3)
	v_add_f32_e32 v79, v79, v94
	s_waitcnt lgkmcnt(2)
	v_add_f32_e32 v80, v80, v95
	s_waitcnt lgkmcnt(1)
	v_add_f32_e32 v81, v81, v96
	s_waitcnt lgkmcnt(0)
	v_add_f32_e32 v82, v82, v97
	s_and_saveexec_b64 s[12:13], vcc
	v_mov_b32_e32 v98, s2
	ds_write_b32 v98, v68 offset:120
	ds_write_b32 v98, v69 offset:124
	ds_write_b32 v98, v70 offset:128
	ds_write_b32 v98, v71 offset:132
	ds_write_b32 v98, v72 offset:136
	ds_write_b32 v98, v73 offset:140
	ds_write_b32 v98, v74 offset:144
	ds_write_b32 v98, v75 offset:148
	ds_write_b32 v98, v76 offset:152
	ds_write_b32 v98, v77 offset:156
	ds_write_b32 v98, v78 offset:160
	ds_write_b32 v98, v79 offset:164
	ds_write_b32 v98, v80 offset:168
	ds_write_b32 v98, v81 offset:172
	ds_write_b32 v98, v82 offset:176
	s_or_b64 exec, exec, s[12:13]
	v_fma_f32 v68, v3, v56, 0
	v_fmac_f32_e32 v68, v7, v57
	v_fma_f32 v69, v4, v56, 0
	v_fmac_f32_e32 v69, v8, v57
	v_fma_f32 v70, v5, v56, 0
	v_fmac_f32_e32 v70, v9, v57
	v_mul_f32_e32 v56, 0xbfb8aa3b, v55
	v_exp_f32_e32 v56, v56
	s_waitcnt lgkmcnt(0)
	v_mul_f32_e32 v57, 0xbfb8aa3b, v54
	v_exp_f32_e32 v57, v57
	v_add_f32_e32 v56, 1.0, v56
	v_rcp_f32_e32 v56, v56
	v_add_f32_e32 v57, 1.0, v57
	v_rcp_f32_e32 v57, v57
	v_mul_f32_e32 v55, v55, v56
	v_fma_f32 v71, v18, v55, 0
	v_mul_f32_e32 v18, v54, v57
	v_fmac_f32_e32 v71, v22, v18
	v_fma_f32 v72, v19, v55, 0
	v_fmac_f32_e32 v72, v23, v18
	v_fma_f32 v73, v20, v55, 0
	v_fmac_f32_e32 v73, v24, v18
	v_fma_f32 v74, v21, v55, 0
	v_fmac_f32_e32 v74, v25, v18
	v_fma_f32 v75, v10, v55, 0
	v_fmac_f32_e32 v75, v14, v18
	v_fma_f32 v76, v11, v55, 0
	v_fmac_f32_e32 v76, v15, v18
	v_fma_f32 v77, v12, v55, 0
	v_fmac_f32_e32 v77, v16, v18
	v_fma_f32 v78, v13, v55, 0
	v_fmac_f32_e32 v78, v17, v18
	v_fma_f32 v79, v2, v55, 0
	v_fmac_f32_e32 v79, v6, v18
	v_fma_f32 v80, v3, v55, 0
	v_fmac_f32_e32 v80, v7, v18
	v_fma_f32 v81, v4, v55, 0
	v_fmac_f32_e32 v81, v8, v18
	v_fma_f32 v82, v5, v55, 0
	v_fmac_f32_e32 v82, v9, v18
	ds_bpermute_b32 v83, v1, v68
	ds_bpermute_b32 v84, v1, v69
	ds_bpermute_b32 v85, v1, v70
	ds_bpermute_b32 v86, v1, v71
	ds_bpermute_b32 v87, v1, v72
	ds_bpermute_b32 v88, v1, v73
	ds_bpermute_b32 v89, v1, v74
	ds_bpermute_b32 v90, v1, v75
	ds_bpermute_b32 v91, v1, v76
	ds_bpermute_b32 v92, v1, v77
	ds_bpermute_b32 v93, v1, v78
	ds_bpermute_b32 v94, v1, v79
	ds_bpermute_b32 v95, v1, v80
	ds_bpermute_b32 v96, v1, v81
	ds_bpermute_b32 v97, v1, v82
	s_waitcnt lgkmcnt(14)
	v_add_f32_e32 v68, v68, v83
	s_waitcnt lgkmcnt(13)
	v_add_f32_e32 v69, v69, v84
	s_waitcnt lgkmcnt(12)
	v_add_f32_e32 v70, v70, v85
	s_waitcnt lgkmcnt(11)
	v_add_f32_e32 v71, v71, v86
	s_waitcnt lgkmcnt(10)
	v_add_f32_e32 v72, v72, v87
	s_waitcnt lgkmcnt(9)
	v_add_f32_e32 v73, v73, v88
	s_waitcnt lgkmcnt(8)
	v_add_f32_e32 v74, v74, v89
	s_waitcnt lgkmcnt(7)
	v_add_f32_e32 v75, v75, v90
	s_waitcnt lgkmcnt(6)
	v_add_f32_e32 v76, v76, v91
	s_waitcnt lgkmcnt(5)
	v_add_f32_e32 v77, v77, v92
	s_waitcnt lgkmcnt(4)
	v_add_f32_e32 v78, v78, v93
	s_waitcnt lgkmcnt(3)
	v_add_f32_e32 v79, v79, v94
	s_waitcnt lgkmcnt(2)
	v_add_f32_e32 v80, v80, v95
	s_waitcnt lgkmcnt(1)
	v_add_f32_e32 v81, v81, v96
	s_waitcnt lgkmcnt(0)
	v_add_f32_e32 v82, v82, v97
	ds_bpermute_b32 v83, v46, v68
	ds_bpermute_b32 v84, v46, v69
	ds_bpermute_b32 v85, v46, v70
	ds_bpermute_b32 v86, v46, v71
	ds_bpermute_b32 v87, v46, v72
	ds_bpermute_b32 v88, v46, v73
	ds_bpermute_b32 v89, v46, v74
	ds_bpermute_b32 v90, v46, v75
	ds_bpermute_b32 v91, v46, v76
	ds_bpermute_b32 v92, v46, v77
	ds_bpermute_b32 v93, v46, v78
	ds_bpermute_b32 v94, v46, v79
	ds_bpermute_b32 v95, v46, v80
	ds_bpermute_b32 v96, v46, v81
	ds_bpermute_b32 v97, v46, v82
	s_waitcnt lgkmcnt(14)
	v_add_f32_e32 v68, v68, v83
	s_waitcnt lgkmcnt(13)
	v_add_f32_e32 v69, v69, v84
	s_waitcnt lgkmcnt(12)
	v_add_f32_e32 v70, v70, v85
	s_waitcnt lgkmcnt(11)
	v_add_f32_e32 v71, v71, v86
	s_waitcnt lgkmcnt(10)
	v_add_f32_e32 v72, v72, v87
	s_waitcnt lgkmcnt(9)
	v_add_f32_e32 v73, v73, v88
	s_waitcnt lgkmcnt(8)
	v_add_f32_e32 v74, v74, v89
	s_waitcnt lgkmcnt(7)
	v_add_f32_e32 v75, v75, v90
	s_waitcnt lgkmcnt(6)
	v_add_f32_e32 v76, v76, v91
	s_waitcnt lgkmcnt(5)
	v_add_f32_e32 v77, v77, v92
	s_waitcnt lgkmcnt(4)
	v_add_f32_e32 v78, v78, v93
	s_waitcnt lgkmcnt(3)
	v_add_f32_e32 v79, v79, v94
	s_waitcnt lgkmcnt(2)
	v_add_f32_e32 v80, v80, v95
	s_waitcnt lgkmcnt(1)
	v_add_f32_e32 v81, v81, v96
	s_waitcnt lgkmcnt(0)
	v_add_f32_e32 v82, v82, v97
	ds_bpermute_b32 v83, v47, v68
	ds_bpermute_b32 v84, v47, v69
	ds_bpermute_b32 v85, v47, v70
	ds_bpermute_b32 v86, v47, v71
	ds_bpermute_b32 v87, v47, v72
	ds_bpermute_b32 v88, v47, v73
	ds_bpermute_b32 v89, v47, v74
	ds_bpermute_b32 v90, v47, v75
	ds_bpermute_b32 v91, v47, v76
	ds_bpermute_b32 v92, v47, v77
	ds_bpermute_b32 v93, v47, v78
	ds_bpermute_b32 v94, v47, v79
	ds_bpermute_b32 v95, v47, v80
	ds_bpermute_b32 v96, v47, v81
	ds_bpermute_b32 v97, v47, v82
	s_waitcnt lgkmcnt(14)
	v_add_f32_e32 v68, v68, v83
	s_waitcnt lgkmcnt(13)
	v_add_f32_e32 v69, v69, v84
	s_waitcnt lgkmcnt(12)
	v_add_f32_e32 v70, v70, v85
	s_waitcnt lgkmcnt(11)
	v_add_f32_e32 v71, v71, v86
	s_waitcnt lgkmcnt(10)
	v_add_f32_e32 v72, v72, v87
	s_waitcnt lgkmcnt(9)
	v_add_f32_e32 v73, v73, v88
	s_waitcnt lgkmcnt(8)
	v_add_f32_e32 v74, v74, v89
	s_waitcnt lgkmcnt(7)
	v_add_f32_e32 v75, v75, v90
	s_waitcnt lgkmcnt(6)
	v_add_f32_e32 v76, v76, v91
	s_waitcnt lgkmcnt(5)
	v_add_f32_e32 v77, v77, v92
	s_waitcnt lgkmcnt(4)
	v_add_f32_e32 v78, v78, v93
	s_waitcnt lgkmcnt(3)
	v_add_f32_e32 v79, v79, v94
	s_waitcnt lgkmcnt(2)
	v_add_f32_e32 v80, v80, v95
	s_waitcnt lgkmcnt(1)
	v_add_f32_e32 v81, v81, v96
	s_waitcnt lgkmcnt(0)
	v_add_f32_e32 v82, v82, v97
	ds_bpermute_b32 v83, v48, v68
	ds_bpermute_b32 v84, v48, v69
	ds_bpermute_b32 v85, v48, v70
	ds_bpermute_b32 v86, v48, v71
	ds_bpermute_b32 v87, v48, v72
	ds_bpermute_b32 v88, v48, v73
	ds_bpermute_b32 v89, v48, v74
	ds_bpermute_b32 v90, v48, v75
	ds_bpermute_b32 v91, v48, v76
	ds_bpermute_b32 v92, v48, v77
	ds_bpermute_b32 v93, v48, v78
	ds_bpermute_b32 v94, v48, v79
	ds_bpermute_b32 v95, v48, v80
	ds_bpermute_b32 v96, v48, v81
	ds_bpermute_b32 v97, v48, v82
	s_waitcnt lgkmcnt(14)
	v_add_f32_e32 v68, v68, v83
	s_waitcnt lgkmcnt(13)
	v_add_f32_e32 v69, v69, v84
	s_waitcnt lgkmcnt(12)
	v_add_f32_e32 v70, v70, v85
	s_waitcnt lgkmcnt(11)
	v_add_f32_e32 v71, v71, v86
	s_waitcnt lgkmcnt(10)
	v_add_f32_e32 v72, v72, v87
	s_waitcnt lgkmcnt(9)
	v_add_f32_e32 v73, v73, v88
	s_waitcnt lgkmcnt(8)
	v_add_f32_e32 v74, v74, v89
	s_waitcnt lgkmcnt(7)
	v_add_f32_e32 v75, v75, v90
	s_waitcnt lgkmcnt(6)
	v_add_f32_e32 v76, v76, v91
	s_waitcnt lgkmcnt(5)
	v_add_f32_e32 v77, v77, v92
	s_waitcnt lgkmcnt(4)
	v_add_f32_e32 v78, v78, v93
	s_waitcnt lgkmcnt(3)
	v_add_f32_e32 v79, v79, v94
	s_waitcnt lgkmcnt(2)
	v_add_f32_e32 v80, v80, v95
	s_waitcnt lgkmcnt(1)
	v_add_f32_e32 v81, v81, v96
	s_waitcnt lgkmcnt(0)
	v_add_f32_e32 v82, v82, v97
	ds_bpermute_b32 v83, v49, v68
	ds_bpermute_b32 v84, v49, v69
	ds_bpermute_b32 v85, v49, v70
	ds_bpermute_b32 v86, v49, v71
	ds_bpermute_b32 v87, v49, v72
	ds_bpermute_b32 v88, v49, v73
	ds_bpermute_b32 v89, v49, v74
	ds_bpermute_b32 v90, v49, v75
	ds_bpermute_b32 v91, v49, v76
	ds_bpermute_b32 v92, v49, v77
	ds_bpermute_b32 v93, v49, v78
	ds_bpermute_b32 v94, v49, v79
	ds_bpermute_b32 v95, v49, v80
	ds_bpermute_b32 v96, v49, v81
	ds_bpermute_b32 v97, v49, v82
	s_waitcnt lgkmcnt(14)
	v_add_f32_e32 v68, v68, v83
	s_waitcnt lgkmcnt(13)
	v_add_f32_e32 v69, v69, v84
	s_waitcnt lgkmcnt(12)
	v_add_f32_e32 v70, v70, v85
	s_waitcnt lgkmcnt(11)
	v_add_f32_e32 v71, v71, v86
	s_waitcnt lgkmcnt(10)
	v_add_f32_e32 v72, v72, v87
	s_waitcnt lgkmcnt(9)
	v_add_f32_e32 v73, v73, v88
	s_waitcnt lgkmcnt(8)
	v_add_f32_e32 v74, v74, v89
	s_waitcnt lgkmcnt(7)
	v_add_f32_e32 v75, v75, v90
	s_waitcnt lgkmcnt(6)
	v_add_f32_e32 v76, v76, v91
	s_waitcnt lgkmcnt(5)
	v_add_f32_e32 v77, v77, v92
	s_waitcnt lgkmcnt(4)
	v_add_f32_e32 v78, v78, v93
	s_waitcnt lgkmcnt(3)
	v_add_f32_e32 v79, v79, v94
	s_waitcnt lgkmcnt(2)
	v_add_f32_e32 v80, v80, v95
	s_waitcnt lgkmcnt(1)
	v_add_f32_e32 v81, v81, v96
	s_waitcnt lgkmcnt(0)
	v_add_f32_e32 v82, v82, v97
	ds_bpermute_b32 v83, v50, v68
	ds_bpermute_b32 v84, v50, v69
	ds_bpermute_b32 v85, v50, v70
	ds_bpermute_b32 v86, v50, v71
	ds_bpermute_b32 v87, v50, v72
	ds_bpermute_b32 v88, v50, v73
	ds_bpermute_b32 v89, v50, v74
	ds_bpermute_b32 v90, v50, v75
	ds_bpermute_b32 v91, v50, v76
	ds_bpermute_b32 v92, v50, v77
	ds_bpermute_b32 v93, v50, v78
	ds_bpermute_b32 v94, v50, v79
	ds_bpermute_b32 v95, v50, v80
	ds_bpermute_b32 v96, v50, v81
	ds_bpermute_b32 v97, v50, v82
	s_waitcnt lgkmcnt(14)
	v_add_f32_e32 v68, v68, v83
	s_waitcnt lgkmcnt(13)
	v_add_f32_e32 v69, v69, v84
	s_waitcnt lgkmcnt(12)
	v_add_f32_e32 v70, v70, v85
	s_waitcnt lgkmcnt(11)
	v_add_f32_e32 v71, v71, v86
	s_waitcnt lgkmcnt(10)
	v_add_f32_e32 v72, v72, v87
	s_waitcnt lgkmcnt(9)
	v_add_f32_e32 v73, v73, v88
	s_waitcnt lgkmcnt(8)
	v_add_f32_e32 v74, v74, v89
	s_waitcnt lgkmcnt(7)
	v_add_f32_e32 v75, v75, v90
	s_waitcnt lgkmcnt(6)
	v_add_f32_e32 v76, v76, v91
	s_waitcnt lgkmcnt(5)
	v_add_f32_e32 v77, v77, v92
	s_waitcnt lgkmcnt(4)
	v_add_f32_e32 v78, v78, v93
	s_waitcnt lgkmcnt(3)
	v_add_f32_e32 v79, v79, v94
	s_waitcnt lgkmcnt(2)
	v_add_f32_e32 v80, v80, v95
	s_waitcnt lgkmcnt(1)
	v_add_f32_e32 v81, v81, v96
	s_waitcnt lgkmcnt(0)
	v_add_f32_e32 v82, v82, v97
	s_and_saveexec_b64 s[12:13], vcc
	v_mov_b32_e32 v98, s2
	ds_write_b32 v98, v68 offset:180
	ds_write_b32 v98, v69 offset:184
	ds_write_b32 v98, v70 offset:188
	ds_write_b32 v98, v71 offset:192
	ds_write_b32 v98, v72 offset:196
	ds_write_b32 v98, v73 offset:200
	ds_write_b32 v98, v74 offset:204
	ds_write_b32 v98, v75 offset:208
	ds_write_b32 v98, v76 offset:212
	ds_write_b32 v98, v77 offset:216
	ds_write_b32 v98, v78 offset:220
	ds_write_b32 v98, v79 offset:224
	ds_write_b32 v98, v80 offset:228
	ds_write_b32 v98, v81 offset:232
	ds_write_b32 v98, v82 offset:236
	s_or_b64 exec, exec, s[12:13]
.LBB0_129:
	s_or_b64 exec, exec, s[12:13]
	s_waitcnt lgkmcnt(0)
	s_barrier
	s_and_saveexec_b64 s[12:13], s[4:5]
	s_cbranch_execz .LBB0_8
	ds_read2_b32 v[2:3], v51 offset1:60
	ds_read2_b32 v[4:5], v51 offset0:120 offset1:180
	v_add_u32_e32 v7, 0x200, v51
	v_add_u32_e32 v10, 0x400, v51
	ds_read2_b32 v[8:9], v7 offset0:112 offset1:172
	ds_read2_b32 v[10:11], v10 offset0:104 offset1:164
	s_waitcnt lgkmcnt(3)
	v_add_f32_e32 v2, 0, v2
	v_add_f32_e32 v2, v2, v3
	s_waitcnt lgkmcnt(2)
	v_add_f32_e32 v2, v2, v4
	v_add_f32_e32 v2, v2, v5
	s_waitcnt lgkmcnt(1)
	v_add_f32_e32 v2, v2, v8
	v_add_f32_e32 v2, v2, v9
	v_add_u32_e32 v6, s10, v53
	s_waitcnt lgkmcnt(0)
	v_add_f32_e32 v2, v2, v10
	v_ashrrev_i32_e32 v7, 31, v6
	v_add_f32_e32 v2, v2, v11
	s_waitcnt vmcnt(0)
	v_add_f32_e32 v4, v2, v99
	v_lshl_add_u64 v[2:3], v[6:7], 2, s[8:9]
	global_store_dword v[2:3], v4, off
	s_branch .LBB0_8

.LBB0_283:
	global_load_dwordx4 v[26:29], v10, s[20:21]
	global_load_dwordx4 v[30:33], v10, s[20:21] offset:1024
	global_load_dwordx4 v[6:9], v10, s[20:21] offset:2048
	global_load_dwordx4 v[2:5], v10, s[20:21] offset:3072
	s_min_i32 s4, s12, 0x4000
	s_ashr_i32 s4, s4, 12
	s_mul_i32 s20, s4, 0xc00
	s_ashr_i32 s21, s20, 31
	s_lshl_b64 s[20:21], s[20:21], 2
	s_add_u32 s20, s2, s20
	s_addc_u32 s21, s3, s21
	v_lshl_add_u64 v[46:47], s[20:21], 0, v[10:11]
	v_add_co_u32_e32 v16, vcc, s17, v46
	s_lshl_b64 s[0:1], s[0:1], 11
	s_nop 0
	v_addc_co_u32_e32 v17, vcc, 0, v47, vcc
	global_load_dwordx4 v[34:37], v[16:17], off
	global_load_dwordx4 v[38:41], v10, s[20:21]
	global_load_dwordx4 v[42:45], v[12:13], off
	v_lshl_add_u64 v[46:47], v[46:47], 0, s[18:19]
	global_load_dwordx4 v[54:57], v[12:13], off offset:1024
	global_load_dwordx4 v[58:61], v[46:47], off offset:1024
	global_load_dwordx4 v[62:65], v10, s[20:21] offset:1024
	global_load_dwordx4 v[66:69], v[12:13], off offset:2048
	global_load_dwordx4 v[70:73], v[46:47], off offset:2048
	global_load_dwordx4 v[74:77], v10, s[20:21] offset:2048
	global_load_dwordx4 v[78:81], v[12:13], off offset:3072
	global_load_dwordx4 v[82:85], v[46:47], off offset:3072
	global_load_dwordx4 v[86:89], v10, s[20:21] offset:3072
	s_add_u32 s12, s12, s14
	s_addc_u32 s13, s13, s15
	s_add_u32 s6, s6, s8
	s_addc_u32 s7, s7, s9
	s_cmpk_lt_i32 s12, 0x4400
	s_waitcnt vmcnt(15)
	v_mul_f32_e32 v16, v27, v27
	v_mul_f32_e32 v17, v29, v29
	s_waitcnt vmcnt(14)
	v_mul_f32_e32 v25, v31, v31
	v_mul_f32_e32 v48, v33, v33
	s_waitcnt vmcnt(13)
	v_mul_f32_e32 v49, v7, v7
	v_mul_f32_e32 v50, v9, v9
	v_fmac_f32_e32 v16, v26, v26
	v_fmac_f32_e32 v17, v28, v28
	v_fmac_f32_e32 v25, v30, v30
	v_fmac_f32_e32 v48, v32, v32
	s_waitcnt vmcnt(12)
	v_mul_f32_e32 v51, v3, v3
	v_mul_f32_e32 v52, v5, v5
	v_fmac_f32_e32 v49, v6, v6
	v_fmac_f32_e32 v50, v8, v8
	v_add_f32_e32 v16, v16, v17
	v_add_f32_e32 v17, v25, v48
	v_fmac_f32_e32 v51, v2, v2
	v_fmac_f32_e32 v52, v4, v4
	v_add_f32_e32 v25, v49, v50
	v_add_f32_e32 v16, v16, v17
	v_add_f32_e32 v48, v51, v52
	v_add_f32_e32 v16, v16, v25
	v_add_f32_e32 v16, v16, v48
	ds_bpermute_b32 v17, v1, v16
	s_waitcnt vmcnt(11)
	v_add_f32_e32 v34, 1.0, v34
	v_add_f32_e32 v36, 1.0, v36
	v_add_f32_e32 v35, 1.0, v35
	v_add_f32_e32 v37, 1.0, v37
	s_waitcnt lgkmcnt(0)
	v_add_f32_e32 v16, v16, v17
	ds_bpermute_b32 v17, v18, v16
	s_waitcnt lgkmcnt(0)
	v_add_f32_e32 v16, v16, v17
	ds_bpermute_b32 v17, v19, v16
	s_waitcnt lgkmcnt(0)
	v_add_f32_e32 v16, v16, v17
	ds_bpermute_b32 v17, v20, v16
	s_waitcnt lgkmcnt(0)
	v_add_f32_e32 v16, v16, v17
	ds_bpermute_b32 v17, v21, v16
	s_waitcnt lgkmcnt(0)
	v_add_f32_e32 v25, v16, v17
	ds_bpermute_b32 v48, v22, v25
	v_lshl_add_u64 v[16:17], v[14:15], 0, s[0:1]
	s_waitcnt lgkmcnt(0)
	v_add_f32_e32 v25, v25, v48
	v_fmamk_f32 v25, v25, 0x3a800000, v23
	v_mul_f32_e32 v48, 0x4f800000, v25
	v_cmp_gt_f32_e32 vcc, s16, v25
	s_nop 1
	v_cndmask_b32_e32 v25, v25, v48, vcc
	v_sqrt_f32_e32 v48, v25
	s_nop 0
	v_add_u32_e32 v49, -1, v48
	v_add_u32_e32 v50, 1, v48
	v_fma_f32 v51, -v49, v48, v25
	v_fma_f32 v52, -v50, v48, v25
	v_cmp_ge_f32_e64 s[0:1], 0, v51
	s_nop 1
	v_cndmask_b32_e64 v48, v48, v49, s[0:1]
	v_cmp_lt_f32_e64 s[0:1], 0, v52
	s_nop 1
	v_cndmask_b32_e64 v48, v48, v50, s[0:1]
	v_mul_f32_e32 v49, 0x37800000, v48
	v_cndmask_b32_e32 v48, v48, v49, vcc
	v_cmp_class_f32_e32 vcc, v25, v24
	s_nop 1
	v_cndmask_b32_e32 v25, v48, v25, vcc
	v_div_scale_f32 v48, s[0:1], v25, v25, 1.0
	v_rcp_f32_e32 v49, v48
	v_div_scale_f32 v50, vcc, 1.0, v25, 1.0
	v_fma_f32 v51, -v48, v49, 1.0
	v_fmac_f32_e32 v49, v51, v49
	v_mul_f32_e32 v51, v50, v49
	v_fma_f32 v52, -v48, v51, v50
	v_fmac_f32_e32 v51, v52, v49
	v_fma_f32 v48, -v48, v51, v50
	v_div_fmas_f32 v48, v48, v49, v51
	v_div_fixup_f32 v25, v48, v25, 1.0
	v_mul_f32_e32 v26, v26, v25
	v_mul_f32_e32 v28, v28, v25
	v_mul_f32_e32 v27, v27, v25
	v_mul_f32_e32 v29, v29, v25
	s_waitcnt vmcnt(9)
	v_mul_f32_e32 v26, v42, v26
	v_mul_f32_e32 v28, v44, v28
	v_mul_f32_e32 v27, v43, v27
	v_mul_f32_e32 v29, v45, v29
	v_fma_f32 v26, v34, v26, v38
	v_fma_f32 v28, v36, v28, v40
	v_fma_f32 v27, v35, v27, v39
	v_fmac_f32_e32 v41, v37, v29
	v_bfe_u32 v29, v26, 16, 1
	v_bfe_u32 v35, v28, 16, 1
	v_bfe_u32 v34, v27, 16, 1
	v_bfe_u32 v36, v41, 16, 1
	v_add3_u32 v26, v26, v29, s22
	v_add3_u32 v28, v28, v35, s22
	v_add3_u32 v27, v27, v34, s22
	v_add3_u32 v29, v41, v36, s22
	v_lshrrev_b32_e32 v26, 16, v26
	v_lshrrev_b32_e32 v28, 16, v28
	v_and_or_b32 v26, v27, s23, v26
	v_and_or_b32 v27, v29, s23, v28
	global_store_dwordx2 v[16:17], v[26:27], off
	v_mul_f32_e32 v30, v30, v25
	v_mul_f32_e32 v32, v32, v25
	v_mul_f32_e32 v31, v31, v25
	v_mul_f32_e32 v33, v33, v25
	v_mul_f32_e32 v6, v6, v25
	v_mul_f32_e32 v8, v8, v25
	v_mul_f32_e32 v7, v7, v25
	v_mul_f32_e32 v9, v9, v25
	v_mul_f32_e32 v2, v2, v25
	v_mul_f32_e32 v4, v4, v25
	v_mul_f32_e32 v3, v3, v25
	v_mul_f32_e32 v5, v5, v25
	s_waitcnt vmcnt(7)
	v_mul_f32_e32 v26, v54, v30
	v_add_f32_e32 v30, 1.0, v58
	v_mul_f32_e32 v28, v56, v32
	v_add_f32_e32 v32, 1.0, v60
	v_mul_f32_e32 v27, v55, v31
	v_add_f32_e32 v31, 1.0, v59
	v_mul_f32_e32 v29, v57, v33
	v_add_f32_e32 v33, 1.0, v61
	v_fma_f32 v26, v30, v26, v62
	v_fma_f32 v28, v32, v28, v64
	v_fma_f32 v27, v31, v27, v63
	v_fma_f32 v41, v33, v29, v65
	v_bfe_u32 v29, v26, 16, 1
	v_bfe_u32 v31, v28, 16, 1
	v_bfe_u32 v30, v27, 16, 1
	v_bfe_u32 v32, v41, 16, 1
	v_add3_u32 v26, v26, v29, s22
	v_add3_u32 v28, v28, v31, s22
	v_add3_u32 v27, v27, v30, s22
	v_add3_u32 v29, v41, v32, s22
	v_lshrrev_b32_e32 v26, 16, v26
	v_lshrrev_b32_e32 v28, 16, v28
	v_and_or_b32 v26, v27, s23, v26
	v_and_or_b32 v27, v29, s23, v28
	global_store_dwordx2 v[16:17], v[26:27], off offset:512
	s_waitcnt vmcnt(5)
	v_mul_f32_e32 v6, v66, v6
	v_add_f32_e32 v26, 1.0, v70
	v_mul_f32_e32 v8, v68, v8
	v_add_f32_e32 v28, 1.0, v72
	v_mul_f32_e32 v7, v67, v7
	v_add_f32_e32 v27, 1.0, v71
	v_mul_f32_e32 v9, v69, v9
	v_add_f32_e32 v29, 1.0, v73
	v_fma_f32 v6, v6, v26, v74
	v_fma_f32 v8, v8, v28, v76
	v_fma_f32 v7, v7, v27, v75
	v_fma_f32 v37, v9, v29, v77
	v_bfe_u32 v9, v6, 16, 1
	v_bfe_u32 v27, v8, 16, 1
	v_bfe_u32 v26, v7, 16, 1
	v_bfe_u32 v28, v37, 16, 1
	v_add3_u32 v6, v6, v9, s22
	v_add3_u32 v8, v8, v27, s22
	v_add3_u32 v7, v7, v26, s22
	v_add3_u32 v9, v37, v28, s22
	v_lshrrev_b32_e32 v6, 16, v6
	v_lshrrev_b32_e32 v8, 16, v8
	v_and_or_b32 v6, v7, s23, v6
	v_and_or_b32 v7, v9, s23, v8
	global_store_dwordx2 v[16:17], v[6:7], off offset:1024
	s_waitcnt vmcnt(3)
	v_mul_f32_e32 v2, v2, v78
	v_add_f32_e32 v6, 1.0, v82
	v_mul_f32_e32 v4, v4, v80
	v_add_f32_e32 v8, 1.0, v84
	v_mul_f32_e32 v3, v3, v79
	v_add_f32_e32 v7, 1.0, v83
	v_mul_f32_e32 v5, v5, v81
	v_add_f32_e32 v9, 1.0, v85
	v_fma_f32 v2, v2, v6, v86
	v_fma_f32 v4, v4, v8, v88
	v_fma_f32 v3, v3, v7, v87
	v_fma_f32 v33, v5, v9, v89
	v_bfe_u32 v5, v2, 16, 1
	v_bfe_u32 v7, v4, 16, 1
	v_bfe_u32 v6, v3, 16, 1
	v_bfe_u32 v8, v33, 16, 1
	v_add3_u32 v2, v2, v5, s22
	v_add3_u32 v4, v4, v7, s22
	v_add3_u32 v3, v3, v6, s22
	v_add3_u32 v5, v33, v8, s22
	v_lshrrev_b32_e32 v2, 16, v2
	v_lshrrev_b32_e32 v4, 16, v4
	v_and_or_b32 v2, v3, s23, v2
	v_and_or_b32 v3, v5, s23, v4
	global_store_dwordx2 v[16:17], v[2:3], off offset:1536
	s_cbranch_scc0 .LBB0_286
